# v20 + gather: cross-row (xor 16 / xor 32) reduction of the expert dot via v_permlane16_swap / v_permlane32_swap instead of two LDS bpermute round trips
# baseline (speedup 1.0000x reference)
.LBB0_1063:
	s_cmp_lt_u32 s22, 64
	s_cselect_b64 vcc, -1, 0
	v_cndmask_b32_e32 v42, v6, v4, vcc
	s_add_i32 s37, s22, 1
	v_readlane_b32 s23, v42, s22
	s_lshl_b32 s23, s23, 9
	v_readlane_b32 s37, v42, s37
	s_lshl_b32 s49, s37, 9
	buffer_load_dwordx2 v[92:93], v72, s[8:11], s49 offen
	s_add_i32 s38, s22, 2
	buffer_load_dwordx2 v[90:91], v72, s[8:11], s23 offen
	v_readlane_b32 s38, v42, s38
	s_lshl_b32 s38, s38, 9
	s_add_i32 s39, s22, 3
	s_add_i32 s40, s22, 4
	s_add_i32 s41, s22, 5
	s_add_i32 s42, s22, 6
	buffer_load_dwordx2 v[94:95], v72, s[8:11], s38 offen
	s_add_i32 s43, s22, 7
	s_add_i32 s44, s22, 8
	s_add_i32 s45, s22, 9
	s_add_i32 s46, s22, 10
	s_add_i32 s47, s22, 11
	s_add_i32 s48, s22, 12
	s_add_i32 s50, s22, 13
	s_add_i32 s51, s22, 14
	s_add_i32 s37, s22, 15
	v_readlane_b32 s39, v42, s39
	v_readlane_b32 s40, v42, s40
	v_readlane_b32 s41, v42, s41
	v_readlane_b32 s42, v42, s42
	v_readlane_b32 s43, v42, s43
	v_readlane_b32 s44, v42, s44
	v_readlane_b32 s45, v42, s45
	v_readlane_b32 s46, v42, s46
	v_readlane_b32 s47, v42, s47
	v_readlane_b32 s48, v42, s48
	v_readlane_b32 s50, v42, s50
	v_readlane_b32 s51, v42, s51
	v_readlane_b32 s52, v42, s37
	s_lshl_b32 s39, s39, 9
	s_lshl_b32 s40, s40, 9
	s_lshl_b32 s41, s41, 9
	s_lshl_b32 s42, s42, 9
	s_lshl_b32 s43, s43, 9
	s_lshl_b32 s44, s44, 9
	s_lshl_b32 s45, s45, 9
	s_lshl_b32 s46, s46, 9
	s_lshl_b32 s47, s47, 9
	s_lshl_b32 s48, s48, 9
	s_lshl_b32 s50, s50, 9
	s_lshl_b32 s51, s51, 9
	s_lshl_b32 s52, s52, 9
	buffer_load_dwordx2 v[96:97], v72, s[8:11], s39 offen
	buffer_load_dwordx2 v[74:75], v72, s[12:15], s23 offen
	buffer_load_dwordx2 v[70:71], v72, s[12:15], s49 offen
	buffer_load_dwordx2 v[68:69], v72, s[12:15], s38 offen
	buffer_load_dwordx2 v[66:67], v72, s[12:15], s39 offen
	buffer_load_dwordx2 v[98:99], v72, s[8:11], s40 offen
	buffer_load_dwordx2 v[100:101], v72, s[8:11], s41 offen
	buffer_load_dwordx2 v[102:103], v72, s[8:11], s42 offen
	buffer_load_dwordx2 v[104:105], v72, s[8:11], s43 offen
	buffer_load_dwordx2 v[64:65], v72, s[12:15], s40 offen
	buffer_load_dwordx2 v[62:63], v72, s[12:15], s41 offen
	buffer_load_dwordx2 v[60:61], v72, s[12:15], s42 offen
	buffer_load_dwordx2 v[58:59], v72, s[12:15], s43 offen
	buffer_load_dwordx2 v[106:107], v72, s[8:11], s44 offen
	buffer_load_dwordx2 v[108:109], v72, s[8:11], s45 offen
	buffer_load_dwordx2 v[110:111], v72, s[8:11], s46 offen
	buffer_load_dwordx2 v[112:113], v72, s[8:11], s47 offen
	buffer_load_dwordx2 v[56:57], v72, s[12:15], s44 offen
	buffer_load_dwordx2 v[54:55], v72, s[12:15], s45 offen
	buffer_load_dwordx2 v[52:53], v72, s[12:15], s46 offen
	buffer_load_dwordx2 v[50:51], v72, s[12:15], s47 offen
	buffer_load_dwordx2 v[114:115], v72, s[8:11], s48 offen
	buffer_load_dwordx2 v[116:117], v72, s[8:11], s50 offen
	buffer_load_dwordx2 v[80:81], v72, s[8:11], s51 offen
	buffer_load_dwordx2 v[78:79], v72, s[8:11], s52 offen
	buffer_load_dwordx2 v[48:49], v72, s[12:15], s48 offen
	buffer_load_dwordx2 v[46:47], v72, s[12:15], s50 offen
	buffer_load_dwordx2 v[44:45], v72, s[12:15], s51 offen
	buffer_load_dwordx2 v[42:43], v72, s[12:15], s52 offen
	s_waitcnt vmcnt(30)
	v_cvt_scalef32_pk_f32_fp4 v[122:123], v90, 1.0 op_sel:[0,1,0]
	v_cvt_scalef32_pk_f32_fp4 v[118:119], v90, 1.0
	v_cvt_scalef32_pk_f32_fp4 v[124:125], v90, 1.0 op_sel:[1,1,0]
	v_pk_mul_f32 v[122:123], v[122:123], v[14:15]
	v_cvt_scalef32_pk_f32_fp4 v[120:121], v90, 1.0 op_sel:[1,0,0]
	v_pk_fma_f32 v[118:119], v[118:119], v[10:11], v[122:123]
	v_pk_mul_f32 v[122:123], v[124:125], v[16:17]
	v_cvt_scalef32_pk_f32_fp4 v[126:127], v91, 1.0
	v_cvt_scalef32_pk_f32_fp4 v[130:131], v91, 1.0 op_sel:[1,0,0]
	v_pk_fma_f32 v[120:121], v[120:121], v[12:13], v[122:123]
	v_cvt_scalef32_pk_f32_fp4 v[134:135], v91, 1.0 op_sel:[0,1,0]
	v_cvt_scalef32_pk_f32_fp4 v[90:91], v91, 1.0 op_sel:[1,1,0]
	v_pk_fma_f32 v[118:119], v[126:127], v[18:19], v[118:119]
	v_pk_fma_f32 v[120:121], v[130:131], v[20:21], v[120:121]
	v_pk_fma_f32 v[118:119], v[134:135], v[22:23], v[118:119]
	v_pk_fma_f32 v[90:91], v[90:91], v[24:25], v[120:121]
	v_cvt_scalef32_pk_f32_fp4 v[120:121], v92, 1.0 op_sel:[0,1,0]
	v_pk_add_f32 v[90:91], v[118:119], v[90:91]
	v_cvt_scalef32_pk_f32_fp4 v[122:123], v92, 1.0 op_sel:[1,1,0]
	v_add_f32_e32 v89, v90, v91
	v_cvt_scalef32_pk_f32_fp4 v[90:91], v92, 1.0
	v_pk_mul_f32 v[120:121], v[120:121], v[14:15]
	v_cvt_scalef32_pk_f32_fp4 v[118:119], v92, 1.0 op_sel:[1,0,0]
	v_pk_fma_f32 v[90:91], v[90:91], v[10:11], v[120:121]
	v_pk_mul_f32 v[120:121], v[122:123], v[16:17]
	v_cvt_scalef32_pk_f32_fp4 v[124:125], v93, 1.0
	v_cvt_scalef32_pk_f32_fp4 v[126:127], v93, 1.0 op_sel:[1,0,0]
	v_pk_fma_f32 v[118:119], v[118:119], v[12:13], v[120:121]
	v_cvt_scalef32_pk_f32_fp4 v[130:131], v93, 1.0 op_sel:[0,1,0]
	v_cvt_scalef32_pk_f32_fp4 v[92:93], v93, 1.0 op_sel:[1,1,0]
	v_pk_fma_f32 v[90:91], v[124:125], v[18:19], v[90:91]
	v_pk_fma_f32 v[118:119], v[126:127], v[20:21], v[118:119]
	v_pk_fma_f32 v[90:91], v[130:131], v[22:23], v[90:91]
	v_pk_fma_f32 v[92:93], v[92:93], v[24:25], v[118:119]
	s_waitcnt vmcnt(29)
	v_cvt_scalef32_pk_f32_fp4 v[118:119], v94, 1.0 op_sel:[0,1,0]
	v_pk_add_f32 v[90:91], v[90:91], v[92:93]
	v_cvt_scalef32_pk_f32_fp4 v[120:121], v94, 1.0 op_sel:[1,1,0]
	v_add_f32_e32 v129, v90, v91
	v_cvt_scalef32_pk_f32_fp4 v[90:91], v94, 1.0
	v_pk_mul_f32 v[118:119], v[118:119], v[14:15]
	v_cvt_scalef32_pk_f32_fp4 v[92:93], v94, 1.0 op_sel:[1,0,0]
	v_pk_fma_f32 v[90:91], v[90:91], v[10:11], v[118:119]
	v_pk_mul_f32 v[118:119], v[120:121], v[16:17]
	v_cvt_scalef32_pk_f32_fp4 v[122:123], v95, 1.0
	v_cvt_scalef32_pk_f32_fp4 v[124:125], v95, 1.0 op_sel:[1,0,0]
	v_pk_fma_f32 v[92:93], v[92:93], v[12:13], v[118:119]
	v_cvt_scalef32_pk_f32_fp4 v[126:127], v95, 1.0 op_sel:[0,1,0]
	v_cvt_scalef32_pk_f32_fp4 v[94:95], v95, 1.0 op_sel:[1,1,0]
	v_pk_fma_f32 v[90:91], v[122:123], v[18:19], v[90:91]
	v_pk_fma_f32 v[92:93], v[124:125], v[20:21], v[92:93]
	v_pk_fma_f32 v[90:91], v[126:127], v[22:23], v[90:91]
	v_pk_fma_f32 v[92:93], v[94:95], v[24:25], v[92:93]
	s_waitcnt vmcnt(28)
	v_cvt_scalef32_pk_f32_fp4 v[94:95], v96, 1.0 op_sel:[0,1,0]
	v_pk_add_f32 v[90:91], v[90:91], v[92:93]
	v_cvt_scalef32_pk_f32_fp4 v[118:119], v96, 1.0 op_sel:[1,1,0]
	v_add_f32_e32 v126, v90, v91
	v_cvt_scalef32_pk_f32_fp4 v[90:91], v96, 1.0
	v_pk_mul_f32 v[94:95], v[94:95], v[14:15]
	v_cvt_scalef32_pk_f32_fp4 v[92:93], v96, 1.0 op_sel:[1,0,0]
	v_pk_fma_f32 v[90:91], v[90:91], v[10:11], v[94:95]
	v_pk_mul_f32 v[94:95], v[118:119], v[16:17]
	v_cvt_scalef32_pk_f32_fp4 v[120:121], v97, 1.0
	v_cvt_scalef32_pk_f32_fp4 v[122:123], v97, 1.0 op_sel:[1,0,0]
	v_pk_fma_f32 v[92:93], v[92:93], v[12:13], v[94:95]
	v_cvt_scalef32_pk_f32_fp4 v[124:125], v97, 1.0 op_sel:[0,1,0]
	v_cvt_scalef32_pk_f32_fp4 v[96:97], v97, 1.0 op_sel:[1,1,0]
	v_pk_fma_f32 v[90:91], v[120:121], v[18:19], v[90:91]
	v_pk_fma_f32 v[92:93], v[122:123], v[20:21], v[92:93]
	v_pk_fma_f32 v[90:91], v[124:125], v[22:23], v[90:91]
	v_pk_fma_f32 v[92:93], v[96:97], v[24:25], v[92:93]
	s_waitcnt vmcnt(23)
	v_cvt_scalef32_pk_f32_fp4 v[94:95], v98, 1.0 op_sel:[0,1,0]
	v_pk_add_f32 v[90:91], v[90:91], v[92:93]
	v_cvt_scalef32_pk_f32_fp4 v[96:97], v98, 1.0 op_sel:[1,1,0]
	v_add_f32_e32 v124, v90, v91
	v_cvt_scalef32_pk_f32_fp4 v[90:91], v98, 1.0
	v_pk_mul_f32 v[94:95], v[94:95], v[14:15]
	v_cvt_scalef32_pk_f32_fp4 v[92:93], v98, 1.0 op_sel:[1,0,0]
	v_pk_fma_f32 v[90:91], v[90:91], v[10:11], v[94:95]
	v_pk_mul_f32 v[94:95], v[96:97], v[16:17]
	v_cvt_scalef32_pk_f32_fp4 v[118:119], v99, 1.0
	v_cvt_scalef32_pk_f32_fp4 v[120:121], v99, 1.0 op_sel:[1,0,0]
	v_pk_fma_f32 v[92:93], v[92:93], v[12:13], v[94:95]
	v_cvt_scalef32_pk_f32_fp4 v[122:123], v99, 1.0 op_sel:[0,1,0]
	v_cvt_scalef32_pk_f32_fp4 v[98:99], v99, 1.0 op_sel:[1,1,0]
	v_pk_fma_f32 v[90:91], v[118:119], v[18:19], v[90:91]
	v_pk_fma_f32 v[92:93], v[120:121], v[20:21], v[92:93]
	v_pk_fma_f32 v[90:91], v[122:123], v[22:23], v[90:91]
	v_pk_fma_f32 v[92:93], v[98:99], v[24:25], v[92:93]
	s_waitcnt vmcnt(22)
	v_cvt_scalef32_pk_f32_fp4 v[94:95], v100, 1.0 op_sel:[0,1,0]
	v_pk_add_f32 v[90:91], v[90:91], v[92:93]
	v_cvt_scalef32_pk_f32_fp4 v[96:97], v100, 1.0 op_sel:[1,1,0]
	v_add_f32_e32 v122, v90, v91
	v_cvt_scalef32_pk_f32_fp4 v[90:91], v100, 1.0
	v_pk_mul_f32 v[94:95], v[94:95], v[14:15]
	v_cvt_scalef32_pk_f32_fp4 v[92:93], v100, 1.0 op_sel:[1,0,0]
	v_pk_fma_f32 v[90:91], v[90:91], v[10:11], v[94:95]
	v_pk_mul_f32 v[94:95], v[96:97], v[16:17]
	v_cvt_scalef32_pk_f32_fp4 v[98:99], v101, 1.0
	v_cvt_scalef32_pk_f32_fp4 v[118:119], v101, 1.0 op_sel:[1,0,0]
	v_pk_fma_f32 v[92:93], v[92:93], v[12:13], v[94:95]
	v_cvt_scalef32_pk_f32_fp4 v[120:121], v101, 1.0 op_sel:[0,1,0]
	v_cvt_scalef32_pk_f32_fp4 v[100:101], v101, 1.0 op_sel:[1,1,0]
	v_pk_fma_f32 v[90:91], v[98:99], v[18:19], v[90:91]
	v_pk_fma_f32 v[92:93], v[118:119], v[20:21], v[92:93]
	v_pk_fma_f32 v[90:91], v[120:121], v[22:23], v[90:91]
	v_pk_fma_f32 v[92:93], v[100:101], v[24:25], v[92:93]
	s_waitcnt vmcnt(21)
	v_cvt_scalef32_pk_f32_fp4 v[94:95], v102, 1.0 op_sel:[0,1,0]
	v_pk_add_f32 v[90:91], v[90:91], v[92:93]
	v_cvt_scalef32_pk_f32_fp4 v[96:97], v102, 1.0 op_sel:[1,1,0]
	v_add_f32_e32 v120, v90, v91
	v_cvt_scalef32_pk_f32_fp4 v[90:91], v102, 1.0
	v_pk_mul_f32 v[94:95], v[94:95], v[14:15]
	v_cvt_scalef32_pk_f32_fp4 v[92:93], v102, 1.0 op_sel:[1,0,0]
	v_pk_fma_f32 v[90:91], v[90:91], v[10:11], v[94:95]
	v_pk_mul_f32 v[94:95], v[96:97], v[16:17]
	v_cvt_scalef32_pk_f32_fp4 v[98:99], v103, 1.0
	v_cvt_scalef32_pk_f32_fp4 v[100:101], v103, 1.0 op_sel:[1,0,0]
	v_pk_fma_f32 v[92:93], v[92:93], v[12:13], v[94:95]
	v_cvt_scalef32_pk_f32_fp4 v[118:119], v103, 1.0 op_sel:[0,1,0]
	v_cvt_scalef32_pk_f32_fp4 v[102:103], v103, 1.0 op_sel:[1,1,0]
	v_pk_fma_f32 v[90:91], v[98:99], v[18:19], v[90:91]
	v_pk_fma_f32 v[92:93], v[100:101], v[20:21], v[92:93]
	v_pk_fma_f32 v[90:91], v[118:119], v[22:23], v[90:91]
	v_pk_fma_f32 v[92:93], v[102:103], v[24:25], v[92:93]
	s_waitcnt vmcnt(20)
	v_cvt_scalef32_pk_f32_fp4 v[94:95], v104, 1.0 op_sel:[0,1,0]
	v_pk_add_f32 v[90:91], v[90:91], v[92:93]
	v_cvt_scalef32_pk_f32_fp4 v[96:97], v104, 1.0 op_sel:[1,1,0]
	v_add_f32_e32 v118, v90, v91
	v_cvt_scalef32_pk_f32_fp4 v[90:91], v104, 1.0
	v_pk_mul_f32 v[94:95], v[94:95], v[14:15]
	v_cvt_scalef32_pk_f32_fp4 v[92:93], v104, 1.0 op_sel:[1,0,0]
	v_pk_fma_f32 v[90:91], v[90:91], v[10:11], v[94:95]
	v_pk_mul_f32 v[94:95], v[96:97], v[16:17]
	v_cvt_scalef32_pk_f32_fp4 v[98:99], v105, 1.0
	v_cvt_scalef32_pk_f32_fp4 v[100:101], v105, 1.0 op_sel:[1,0,0]
	v_pk_fma_f32 v[92:93], v[92:93], v[12:13], v[94:95]
	v_cvt_scalef32_pk_f32_fp4 v[102:103], v105, 1.0 op_sel:[0,1,0]
	v_cvt_scalef32_pk_f32_fp4 v[104:105], v105, 1.0 op_sel:[1,1,0]
	v_pk_fma_f32 v[90:91], v[98:99], v[18:19], v[90:91]
	v_pk_fma_f32 v[92:93], v[100:101], v[20:21], v[92:93]
	v_pk_fma_f32 v[90:91], v[102:103], v[22:23], v[90:91]
	v_pk_fma_f32 v[92:93], v[104:105], v[24:25], v[92:93]
	s_waitcnt vmcnt(15)
	v_cvt_scalef32_pk_f32_fp4 v[94:95], v106, 1.0 op_sel:[0,1,0]
	v_pk_add_f32 v[90:91], v[90:91], v[92:93]
	v_cvt_scalef32_pk_f32_fp4 v[96:97], v106, 1.0 op_sel:[1,1,0]
	v_add_f32_e32 v119, v90, v91
	v_cvt_scalef32_pk_f32_fp4 v[90:91], v106, 1.0
	v_pk_mul_f32 v[94:95], v[94:95], v[14:15]
	v_cvt_scalef32_pk_f32_fp4 v[92:93], v106, 1.0 op_sel:[1,0,0]
	v_pk_fma_f32 v[90:91], v[90:91], v[10:11], v[94:95]
	v_pk_mul_f32 v[94:95], v[96:97], v[16:17]
	v_cvt_scalef32_pk_f32_fp4 v[98:99], v107, 1.0
	v_cvt_scalef32_pk_f32_fp4 v[100:101], v107, 1.0 op_sel:[1,0,0]
	v_pk_fma_f32 v[92:93], v[92:93], v[12:13], v[94:95]
	v_cvt_scalef32_pk_f32_fp4 v[102:103], v107, 1.0 op_sel:[0,1,0]
	v_cvt_scalef32_pk_f32_fp4 v[104:105], v107, 1.0 op_sel:[1,1,0]
	v_pk_fma_f32 v[90:91], v[98:99], v[18:19], v[90:91]
	v_pk_fma_f32 v[92:93], v[100:101], v[20:21], v[92:93]
	v_pk_fma_f32 v[90:91], v[102:103], v[22:23], v[90:91]
	v_pk_fma_f32 v[92:93], v[104:105], v[24:25], v[92:93]
	s_waitcnt vmcnt(14)
	v_cvt_scalef32_pk_f32_fp4 v[94:95], v108, 1.0 op_sel:[0,1,0]
	v_pk_add_f32 v[90:91], v[90:91], v[92:93]
	v_cvt_scalef32_pk_f32_fp4 v[96:97], v108, 1.0 op_sel:[1,1,0]
	v_add_f32_e32 v106, v90, v91
	v_cvt_scalef32_pk_f32_fp4 v[90:91], v108, 1.0
	v_pk_mul_f32 v[94:95], v[94:95], v[14:15]
	v_cvt_scalef32_pk_f32_fp4 v[92:93], v108, 1.0 op_sel:[1,0,0]
	v_pk_fma_f32 v[90:91], v[90:91], v[10:11], v[94:95]
	v_pk_mul_f32 v[94:95], v[96:97], v[16:17]
	v_cvt_scalef32_pk_f32_fp4 v[98:99], v109, 1.0
	v_cvt_scalef32_pk_f32_fp4 v[100:101], v109, 1.0 op_sel:[1,0,0]
	v_pk_fma_f32 v[92:93], v[92:93], v[12:13], v[94:95]
	v_cvt_scalef32_pk_f32_fp4 v[102:103], v109, 1.0 op_sel:[0,1,0]
	v_cvt_scalef32_pk_f32_fp4 v[104:105], v109, 1.0 op_sel:[1,1,0]
	v_pk_fma_f32 v[90:91], v[98:99], v[18:19], v[90:91]
	v_pk_fma_f32 v[92:93], v[100:101], v[20:21], v[92:93]
	v_pk_fma_f32 v[90:91], v[102:103], v[22:23], v[90:91]
	v_pk_fma_f32 v[92:93], v[104:105], v[24:25], v[92:93]
	s_waitcnt vmcnt(13)
	v_cvt_scalef32_pk_f32_fp4 v[94:95], v110, 1.0 op_sel:[0,1,0]
	v_pk_add_f32 v[90:91], v[90:91], v[92:93]
	v_cvt_scalef32_pk_f32_fp4 v[96:97], v110, 1.0 op_sel:[1,1,0]
	v_add_f32_e32 v107, v90, v91
	v_cvt_scalef32_pk_f32_fp4 v[90:91], v110, 1.0
	v_pk_mul_f32 v[94:95], v[94:95], v[14:15]
	v_cvt_scalef32_pk_f32_fp4 v[92:93], v110, 1.0 op_sel:[1,0,0]
	v_pk_fma_f32 v[90:91], v[90:91], v[10:11], v[94:95]
	v_pk_mul_f32 v[94:95], v[96:97], v[16:17]
	v_cvt_scalef32_pk_f32_fp4 v[98:99], v111, 1.0
	v_cvt_scalef32_pk_f32_fp4 v[100:101], v111, 1.0 op_sel:[1,0,0]
	v_pk_fma_f32 v[92:93], v[92:93], v[12:13], v[94:95]
	v_cvt_scalef32_pk_f32_fp4 v[102:103], v111, 1.0 op_sel:[0,1,0]
	v_cvt_scalef32_pk_f32_fp4 v[104:105], v111, 1.0 op_sel:[1,1,0]
	v_pk_fma_f32 v[90:91], v[98:99], v[18:19], v[90:91]
	v_pk_fma_f32 v[92:93], v[100:101], v[20:21], v[92:93]
	v_pk_fma_f32 v[90:91], v[102:103], v[22:23], v[90:91]
	v_pk_fma_f32 v[92:93], v[104:105], v[24:25], v[92:93]
	s_waitcnt vmcnt(12)
	v_cvt_scalef32_pk_f32_fp4 v[94:95], v112, 1.0 op_sel:[0,1,0]
	v_pk_add_f32 v[90:91], v[90:91], v[92:93]
	v_cvt_scalef32_pk_f32_fp4 v[96:97], v112, 1.0 op_sel:[1,1,0]
	v_add_f32_e32 v108, v90, v91
	v_cvt_scalef32_pk_f32_fp4 v[90:91], v112, 1.0
	v_pk_mul_f32 v[94:95], v[94:95], v[14:15]
	v_cvt_scalef32_pk_f32_fp4 v[92:93], v112, 1.0 op_sel:[1,0,0]
	v_pk_fma_f32 v[90:91], v[90:91], v[10:11], v[94:95]
	v_pk_mul_f32 v[94:95], v[96:97], v[16:17]
	v_cvt_scalef32_pk_f32_fp4 v[98:99], v113, 1.0
	v_cvt_scalef32_pk_f32_fp4 v[100:101], v113, 1.0 op_sel:[1,0,0]
	v_pk_fma_f32 v[92:93], v[92:93], v[12:13], v[94:95]
	v_cvt_scalef32_pk_f32_fp4 v[102:103], v113, 1.0 op_sel:[0,1,0]
	v_cvt_scalef32_pk_f32_fp4 v[104:105], v113, 1.0 op_sel:[1,1,0]
	v_pk_fma_f32 v[90:91], v[98:99], v[18:19], v[90:91]
	v_pk_fma_f32 v[92:93], v[100:101], v[20:21], v[92:93]
	v_pk_fma_f32 v[90:91], v[102:103], v[22:23], v[90:91]
	v_pk_fma_f32 v[92:93], v[104:105], v[24:25], v[92:93]
	s_waitcnt vmcnt(7)
	v_cvt_scalef32_pk_f32_fp4 v[94:95], v114, 1.0 op_sel:[0,1,0]
	v_pk_add_f32 v[90:91], v[90:91], v[92:93]
	v_cvt_scalef32_pk_f32_fp4 v[96:97], v114, 1.0 op_sel:[1,1,0]
	v_add_f32_e32 v109, v90, v91
	v_cvt_scalef32_pk_f32_fp4 v[90:91], v114, 1.0
	v_pk_mul_f32 v[94:95], v[94:95], v[14:15]
	v_cvt_scalef32_pk_f32_fp4 v[92:93], v114, 1.0 op_sel:[1,0,0]
	v_pk_fma_f32 v[90:91], v[90:91], v[10:11], v[94:95]
	v_pk_mul_f32 v[94:95], v[96:97], v[16:17]
	v_cvt_scalef32_pk_f32_fp4 v[98:99], v115, 1.0
	v_cvt_scalef32_pk_f32_fp4 v[100:101], v115, 1.0 op_sel:[1,0,0]
	v_pk_fma_f32 v[92:93], v[92:93], v[12:13], v[94:95]
	v_cvt_scalef32_pk_f32_fp4 v[102:103], v115, 1.0 op_sel:[0,1,0]
	v_cvt_scalef32_pk_f32_fp4 v[104:105], v115, 1.0 op_sel:[1,1,0]
	v_pk_fma_f32 v[90:91], v[98:99], v[18:19], v[90:91]
	v_pk_fma_f32 v[92:93], v[100:101], v[20:21], v[92:93]
	v_pk_fma_f32 v[90:91], v[102:103], v[22:23], v[90:91]
	v_pk_fma_f32 v[92:93], v[104:105], v[24:25], v[92:93]
	s_waitcnt vmcnt(6)
	v_cvt_scalef32_pk_f32_fp4 v[94:95], v116, 1.0 op_sel:[0,1,0]
	v_pk_add_f32 v[90:91], v[90:91], v[92:93]
	v_cvt_scalef32_pk_f32_fp4 v[96:97], v116, 1.0 op_sel:[1,1,0]
	v_add_f32_e32 v110, v90, v91
	v_cvt_scalef32_pk_f32_fp4 v[90:91], v116, 1.0
	v_pk_mul_f32 v[94:95], v[94:95], v[14:15]
	v_cvt_scalef32_pk_f32_fp4 v[92:93], v116, 1.0 op_sel:[1,0,0]
	v_pk_fma_f32 v[90:91], v[90:91], v[10:11], v[94:95]
	v_pk_mul_f32 v[94:95], v[96:97], v[16:17]
	v_cvt_scalef32_pk_f32_fp4 v[98:99], v117, 1.0
	v_cvt_scalef32_pk_f32_fp4 v[100:101], v117, 1.0 op_sel:[1,0,0]
	v_pk_fma_f32 v[92:93], v[92:93], v[12:13], v[94:95]
	v_cvt_scalef32_pk_f32_fp4 v[102:103], v117, 1.0 op_sel:[0,1,0]
	v_cvt_scalef32_pk_f32_fp4 v[104:105], v117, 1.0 op_sel:[1,1,0]
	v_pk_fma_f32 v[90:91], v[98:99], v[18:19], v[90:91]
	v_pk_fma_f32 v[92:93], v[100:101], v[20:21], v[92:93]
	v_pk_fma_f32 v[90:91], v[102:103], v[22:23], v[90:91]
	v_pk_fma_f32 v[92:93], v[104:105], v[24:25], v[92:93]
	s_waitcnt vmcnt(5)
	v_cvt_scalef32_pk_f32_fp4 v[94:95], v80, 1.0 op_sel:[0,1,0]
	v_pk_add_f32 v[90:91], v[90:91], v[92:93]
	v_cvt_scalef32_pk_f32_fp4 v[96:97], v80, 1.0 op_sel:[1,1,0]
	v_add_f32_e32 v104, v90, v91
	v_cvt_scalef32_pk_f32_fp4 v[90:91], v80, 1.0
	v_pk_mul_f32 v[94:95], v[94:95], v[14:15]
	v_cvt_scalef32_pk_f32_fp4 v[92:93], v80, 1.0 op_sel:[1,0,0]
	v_pk_fma_f32 v[90:91], v[90:91], v[10:11], v[94:95]
	v_pk_mul_f32 v[94:95], v[96:97], v[16:17]
	v_cvt_scalef32_pk_f32_fp4 v[98:99], v81, 1.0
	v_cvt_scalef32_pk_f32_fp4 v[100:101], v81, 1.0 op_sel:[1,0,0]
	v_pk_fma_f32 v[92:93], v[92:93], v[12:13], v[94:95]
	v_cvt_scalef32_pk_f32_fp4 v[102:103], v81, 1.0 op_sel:[0,1,0]
	v_cvt_scalef32_pk_f32_fp4 v[80:81], v81, 1.0 op_sel:[1,1,0]
	v_pk_fma_f32 v[90:91], v[98:99], v[18:19], v[90:91]
	v_pk_fma_f32 v[92:93], v[100:101], v[20:21], v[92:93]
	v_pk_fma_f32 v[90:91], v[102:103], v[22:23], v[90:91]
	v_pk_fma_f32 v[80:81], v[80:81], v[24:25], v[92:93]
	s_waitcnt vmcnt(4)
	v_cvt_scalef32_pk_f32_fp4 v[92:93], v78, 1.0 op_sel:[0,1,0]
	v_pk_add_f32 v[80:81], v[90:91], v[80:81]
	v_cvt_scalef32_pk_f32_fp4 v[94:95], v78, 1.0 op_sel:[1,1,0]
	v_add_f32_e32 v102, v80, v81
	v_cvt_scalef32_pk_f32_fp4 v[80:81], v78, 1.0
	v_pk_mul_f32 v[92:93], v[92:93], v[14:15]
	v_cvt_scalef32_pk_f32_fp4 v[90:91], v78, 1.0 op_sel:[1,0,0]
	v_pk_fma_f32 v[80:81], v[80:81], v[10:11], v[92:93]
	v_pk_mul_f32 v[92:93], v[94:95], v[16:17]
	v_cvt_scalef32_pk_f32_fp4 v[96:97], v79, 1.0
	v_cvt_scalef32_pk_f32_fp4 v[98:99], v79, 1.0 op_sel:[1,0,0]
	v_pk_fma_f32 v[90:91], v[90:91], v[12:13], v[92:93]
	v_cvt_scalef32_pk_f32_fp4 v[100:101], v79, 1.0 op_sel:[0,1,0]
	v_cvt_scalef32_pk_f32_fp4 v[78:79], v79, 1.0 op_sel:[1,1,0]
	v_pk_fma_f32 v[80:81], v[96:97], v[18:19], v[80:81]
	v_pk_fma_f32 v[90:91], v[98:99], v[20:21], v[90:91]
	v_pk_fma_f32 v[80:81], v[100:101], v[22:23], v[80:81]
	v_pk_fma_f32 v[78:79], v[78:79], v[24:25], v[90:91]
	v_cndmask_b32_e64 v90, v124, v109, s[0:1]
	v_pk_add_f32 v[78:79], v[80:81], v[78:79]
	v_cndmask_b32_e64 v80, v89, v106, s[0:1]
	v_add_f32_e32 v78, v78, v79
	v_cndmask_b32_e64 v79, v106, v89, s[0:1]
	v_cndmask_b32_e64 v81, v129, v107, s[0:1]
	v_cndmask_b32_e64 v89, v126, v108, s[0:1]
	v_add_f32_dpp v79, v80, v79 row_ror:8 row_mask:0xf bank_mask:0xf bound_ctrl:1
	v_cndmask_b32_e64 v80, v107, v129, s[0:1]
	v_cndmask_b32_e64 v91, v122, v110, s[0:1]
	v_cndmask_b32_e64 v92, v120, v104, s[0:1]
	v_add_f32_dpp v80, v81, v80 row_ror:8 row_mask:0xf bank_mask:0xf bound_ctrl:1
	v_cndmask_b32_e64 v81, v108, v126, s[0:1]
	v_cndmask_b32_e64 v93, v118, v102, s[0:1]
	s_nop 0
	v_add_f32_dpp v81, v89, v81 row_ror:8 row_mask:0xf bank_mask:0xf bound_ctrl:1
	v_cndmask_b32_e64 v89, v109, v124, s[0:1]
	s_nop 1
	v_add_f32_dpp v89, v90, v89 row_ror:8 row_mask:0xf bank_mask:0xf bound_ctrl:1
	v_cndmask_b32_e64 v90, v110, v122, s[0:1]
	s_nop 1
	v_add_f32_dpp v90, v91, v90 row_ror:8 row_mask:0xf bank_mask:0xf bound_ctrl:1
	v_cndmask_b32_e64 v91, v104, v120, s[0:1]
	s_nop 1
	v_add_f32_dpp v91, v92, v91 row_ror:8 row_mask:0xf bank_mask:0xf bound_ctrl:1
	v_cndmask_b32_e64 v92, v102, v118, s[0:1]
	s_nop 1
	v_add_f32_dpp v92, v93, v92 row_ror:8 row_mask:0xf bank_mask:0xf bound_ctrl:1
	v_cndmask_b32_e64 v93, v78, v119, s[0:1]
	v_cndmask_b32_e64 v78, v119, v78, s[0:1]
	s_nop 1
	v_add_f32_dpp v78, v78, v93 row_ror:8 row_mask:0xf bank_mask:0xf bound_ctrl:1
	v_cndmask_b32_e64 v93, v90, v79, s[2:3]
	v_cndmask_b32_e64 v79, v79, v90, s[2:3]
	v_cndmask_b32_e64 v90, v91, v80, s[2:3]
	v_cndmask_b32_e64 v80, v80, v91, s[2:3]
	v_add_f32_dpp v79, v79, v93 row_half_mirror row_mask:0xf bank_mask:0xf bound_ctrl:1
	s_nop 0
	v_add_f32_dpp v80, v80, v90 row_half_mirror row_mask:0xf bank_mask:0xf bound_ctrl:1
	v_cndmask_b32_e64 v90, v92, v81, s[2:3]
	v_cndmask_b32_e64 v81, v81, v92, s[2:3]
	s_nop 1
	v_add_f32_dpp v81, v81, v90 row_half_mirror row_mask:0xf bank_mask:0xf bound_ctrl:1
	v_cndmask_b32_e64 v90, v78, v89, s[2:3]
	v_cndmask_b32_e64 v78, v89, v78, s[2:3]
	v_cndmask_b32_e64 v89, v81, v79, s[4:5]
	v_cndmask_b32_e64 v79, v79, v81, s[4:5]
	v_add_f32_dpp v78, v78, v90 row_half_mirror row_mask:0xf bank_mask:0xf bound_ctrl:1
	v_cndmask_b32_e64 v81, v78, v80, s[4:5]
	v_cndmask_b32_e64 v78, v80, v78, s[4:5]
	v_add_f32_dpp v79, v79, v89 quad_perm:[2,3,0,1] row_mask:0xf bank_mask:0xf bound_ctrl:1
	s_nop 0
	v_add_f32_dpp v78, v78, v81 quad_perm:[2,3,0,1] row_mask:0xf bank_mask:0xf bound_ctrl:1
	v_cndmask_b32_e64 v80, v78, v79, s[6:7]
	v_cndmask_b32_e64 v78, v79, v78, s[6:7]
	v_and_or_b32 v81, s22, 48, v83
	v_lshlrev_b32_e32 v81, 2, v81
	v_add_f32_dpp v78, v78, v80 quad_perm:[1,0,3,2] row_mask:0xf bank_mask:0xf bound_ctrl:1
	v_cndmask_b32_e32 v90, v7, v5, vcc
	v_cndmask_b32_e32 v91, v88, v87, vcc
	ds_bpermute_b32 v89, v81, v90
	v_mov_b32_e32 v79, v78
	s_nop 1
	v_permlane16_swap_b32_e32 v79, v78
	s_nop 1
	v_add_f32_e32 v79, v78, v79
	s_nop 0
	v_mov_b32_e32 v80, v79
	s_nop 1
	v_permlane32_swap_b32_e32 v80, v79
	s_nop 1
	v_add_f32_e32 v79, v79, v80
	ds_bpermute_b32 v78, v81, v91
	s_waitcnt lgkmcnt(1)
	v_mul_f32_e32 v79, v79, v89
	v_mul_f32_e32 v80, 0x3f3504f3, v79
	v_cmp_nlt_f32_e64 s[22:23], |v80|, 1.0
	s_and_saveexec_b64 s[38:39], s[22:23]
	s_xor_b64 s[22:23], exec, s[38:39]
	s_cbranch_execz .LBB0_1065
	v_fma_f32 v81, |v80|, s24, v85
	v_fma_f32 v81, |v80|, v81, s25
	v_fma_f32 v81, |v80|, v81, s26
	v_fma_f32 v81, |v80|, v81, s27
	v_fma_f32 v81, |v80|, v81, s28
	v_fma_f32 v81, |v80|, v81, s29
	v_fma_f32 v81, |v80|, v81, |v80|
	v_mul_f32_e32 v89, 0xbfb8aa3b, v81
	v_fma_f32 v90, v81, s30, -v89
	v_rndne_f32_e32 v91, v89
	v_fmac_f32_e32 v90, 0xb2a5705f, v81
	v_sub_f32_e32 v89, v89, v91
	v_add_f32_e32 v89, v89, v90
	v_cvt_i32_f32_e32 v90, v91
	v_exp_f32_e32 v89, v89
	v_cmp_nlt_f32_e32 vcc, s31, v81
	v_ldexp_f32 v89, v89, v90
	s_nop 0
	v_cndmask_b32_e32 v89, 0, v89, vcc
	v_cmp_ngt_f32_e32 vcc, s33, v81
	s_nop 1
	v_cndmask_b32_e32 v81, v86, v89, vcc
	v_sub_f32_e32 v81, 1.0, v81
